# v16 + w_in_a transpose tile counts by arrival rank inside the conversion phase (8/7/7/6/6/6/5/3)
# speedup vs baseline: 1.0018x; 1.0018x over previous
; __device__ __forceinline__ u32x4 pack8(const f32x4 a, const f32x4 b) { u32x4 w; w.x = cvt_pk_bf16(a[0], a[1]); w.y = cvt_pk_bf16(a[2], a[3]); w.z = cvt_pk_bf16(b[0], b[1]); w.w = cvt_pk_bf16(b[2], b[3]); return w; }
; __device__ __forceinline__ void convert_flat(const float* src, bf16_t* dst, size_t n, int G, int bid) {
;     const size_t n8 = n / 8, stride = (size_t)G * NTHREADS;
;     size_t i = (size_t)bid * NTHREADS + threadIdx.x;
;     for (; i + 3 * stride < n8; i += 4 * stride) {
;         f32x4 a[4], b[4];
; #pragma unroll
;         for (int u = 0; u < 4; ++u) { a[u] = __builtin_nontemporal_load((const f32x4*)(src + (i + u * stride) * 8)); b[u] = __builtin_nontemporal_load((const f32x4*)(src + (i + u * stride) * 8 + 4)); }
; #pragma unroll
;         for (int u = 0; u < 4; ++u) *(u32x4*)(dst + (i + u * stride) * 8) = pack8(a[u], b[u]);
;     }
; __global__ void __launch_bounds__(NTHREADS, 2) mk_fwd(Params P) {
;     ...
;         convert_flat(P.p, PB, (size_t)2 * MTOK * 256, G, bid);
.LBB0_48:
	s_and_saveexec_b64 s[100:101], s[12:13]
	s_cbranch_execz .Lrk0_a
	v_mov_b32_e32 v253, 0xa1e0
	v_mov_b32_e32 v254, 1
	global_atomic_add v255, v253, v254, s[54:55] sc0
.Lrk0_a:
	s_or_b64 exec, exec, s[100:101]
	s_ashr_i32 s3, s2, 31
	s_lshl_b64 s[10:11], s[2:3], 9
	v_mov_b32_e32 v165, 0
	v_lshl_add_u64 v[16:17], s[10:11], 0, v[164:165]
	s_waitcnt vmcnt(5)
	v_mov_b32_e32 v0, 0x600
	v_mad_i64_i32 v[18:19], s[36:37], s34, v0, v[16:17]
	s_ashr_i32 s5, s34, 31
	s_mov_b32 s4, s34
	s_mov_b64 s[36:37], 0x80000
	s_lshl_b64 s[0:1], s[4:5], 9
	s_mul_hi_i32 s7, s34, 0x600
	s_mul_i32 s6, s34, 0x600
	v_cmp_gt_u64_e32 vcc, s[36:37], v[18:19]
	v_mov_b64_e32 v[0:1], v[16:17]
	s_barrier
	s_and_saveexec_b64 s[36:37], vcc
	s_cbranch_execz .LBB0_52
	s_lshl_b64 s[60:61], s[2:3], 13
	v_lshlrev_b32_e32 v0, 4, v164
	v_mov_b32_e32 v1, v165
	v_lshl_add_u64 v[0:1], s[60:61], 0, v[0:1]
	s_mov_b64 s[60:61], 0x3200000
	v_lshl_add_u64 v[2:3], v[0:1], 0, s[60:61]
	s_lshl_b64 s[60:61], s[4:5], 15
	s_lshl_b64 s[62:63], s[4:5], 10
	s_add_u32 s62, s62, s10
	s_addc_u32 s63, s63, s11
	v_lshl_add_u64 v[0:1], s[62:63], 0, v[164:165]
	s_add_u32 s62, s6, s10
	s_waitcnt vmcnt(3)
	v_mov_b64_e32 v[8:9], 0x3200000
	s_addc_u32 s63, s7, s11
	v_lshl_add_u64 v[4:5], v[0:1], 4, v[8:9]
	v_lshl_add_u64 v[0:1], s[62:63], 0, v[164:165]
	s_add_u32 s62, s10, s0
	s_addc_u32 s63, s11, s1
	v_lshl_add_u64 v[6:7], v[0:1], 4, v[8:9]
	v_lshl_add_u64 v[0:1], s[62:63], 0, v[164:165]
	s_lshl_b64 s[62:63], s[2:3], 14
	s_add_u32 s62, s18, s62
	v_lshl_add_u64 v[8:9], v[0:1], 4, v[8:9]
	v_lshlrev_b32_e32 v0, 5, v164
	v_mov_b32_e32 v1, v165
	s_addc_u32 s63, s19, s63
	v_lshl_add_u64 v[10:11], s[62:63], 0, v[0:1]
	s_lshl_b64 s[62:63], s[4:5], 16
	s_lshl_b64 s[66:67], s[4:5], 14
	s_mov_b64 s[64:65], 0
	s_mov_b64 s[68:69], 0x7ffff
	s_mov_b64 s[70:71], s[40:41]
	v_mov_b64_e32 v[0:1], v[16:17]

; #define LAS __attribute__((address_space(3)))
; template <bool REMAP = false>
; __device__ __forceinline__ void transpose_convert(LAS unsigned char* lds, const float* src, bf16_t* dst, int K, int N, int G, int bid) {
;     LAS float* tile = (LAS float*)lds;
;     const int tid = threadIdx.x, ntn = N / 64, ntiles = (K / 128) * ntn;
;     const int r0 = tid >> 4, c4 = tid & 15;
;     f32x4 v[4];
;     if (bid < ntiles) { const int k0 = (bid / ntn) * 128, n0 = (bid % ntn) * 64;
; #pragma unroll
;         for (int i = 0; i < 4; ++i) v[i] = __builtin_nontemporal_load((const f32x4*)(src + (size_t)(k0 + r0 + 32 * i) * N + n0 + c4 * 4)); }
; __global__ void __launch_bounds__(NTHREADS, 2) mk_fwd(Params P) {
;     ...
;         transpose_convert<true>(lds, P.w_in_a, WINA, 2048, 6144, G, bid);
.LBB0_60:
	s_or_b64 exec, exec, s[18:19]
	s_and_saveexec_b64 s[100:101], s[12:13]
	s_cbranch_execz .Lrk0_n
	s_waitcnt vmcnt(0)
	v_mov_b32_e32 v253, 0x20008
	ds_write_b32 v253, v255
.Lrk0_n:
	s_or_b64 exec, exec, s[100:101]
	s_waitcnt lgkmcnt(0)
	s_barrier
	v_mov_b32_e32 v248, 0x20008
	ds_read_b32 v249, v248
	s_waitcnt lgkmcnt(0)
	v_readfirstlane_b32 s99, v249
	s_and_b32 s99, s99, 0xff
	s_lshr_b32 s18, s99, 5
	s_and_b32 s19, s99, 31
	s_mov_b32 s100, 8
	s_mov_b32 s99, 0
	s_cmp_lt_u32 s18, 1
	s_cbranch_scc1 .Lrk0_done
	s_mov_b32 s100, 7
	s_movk_i32 s99, 256
	s_cmp_lt_u32 s18, 2
	s_cbranch_scc1 .Lrk0_done
	s_mov_b32 s100, 7
	s_movk_i32 s99, 480
	s_cmp_lt_u32 s18, 3
	s_cbranch_scc1 .Lrk0_done
	s_mov_b32 s100, 6
	s_movk_i32 s99, 704
	s_cmp_lt_u32 s18, 4
	s_cbranch_scc1 .Lrk0_done
	s_mov_b32 s100, 6
	s_movk_i32 s99, 896
	s_cmp_lt_u32 s18, 5
	s_cbranch_scc1 .Lrk0_done
	s_mov_b32 s100, 6
	s_movk_i32 s99, 1088
	s_cmp_lt_u32 s18, 6
	s_cbranch_scc1 .Lrk0_done
	s_mov_b32 s100, 5
	s_movk_i32 s99, 1280
	s_cmp_lt_u32 s18, 7
	s_cbranch_scc1 .Lrk0_done
	s_mov_b32 s100, 3
	s_movk_i32 s99, 1440
.Lrk0_done:
	s_mul_i32 s19, s19, s100
	s_add_i32 s99, s99, s19
	s_add_i32 s100, s99, s100
	s_mul_hi_i32 s18, s99, 0x2aaaaaab
	s_lshr_b32 s19, s18, 31
	s_ashr_i32 s18, s18, 4
	s_add_i32 s19, s18, s19
	s_mul_i32 s18, s19, 0x60
	s_sub_i32 s18, s99, s18
	s_lshl_b32 s18, s18, 6
	s_waitcnt vmcnt(2)
	v_lshl_or_b32 v12, s19, 7, v214
	s_ashr_i32 s19, s18, 31
	s_lshl_b64 s[18:19], s[18:19], 2
	v_and_b32_e32 v26, 15, v164
	s_add_u32 s18, s20, s18
	s_addc_u32 s19, s21, s19
	v_lshlrev_b32_e32 v22, 4, v26
	v_mov_b32_e32 v23, 0
	v_lshl_add_u64 v[8:9], s[18:19], 0, v[22:23]
	s_movk_i32 s26, 0x6000
	v_mad_i64_i32 v[0:1], s[18:19], v12, s26, v[8:9]
	v_add_u32_e32 v2, 32, v12
	v_or_b32_e32 v10, 64, v12
	v_add_u32_e32 v12, 0x60, v12
	v_mad_i64_i32 v[4:5], s[18:19], v2, s26, v[8:9]
	v_mad_i64_i32 v[10:11], s[18:19], v10, s26, v[8:9]
	v_mad_i64_i32 v[12:13], s[18:19], v12, s26, v[8:9]
	global_load_dwordx4 v[0:3], v[0:1], off nt
	s_nop 0
	global_load_dwordx4 v[4:7], v[4:5], off nt
	s_nop 0
	global_load_dwordx4 v[8:11], v[10:11], off nt
	s_nop 0
	global_load_dwordx4 v[12:15], v[12:13], off nt
	v_add_u32_e32 v25, 0x200, v164
	v_add_u32_e32 v27, 0, v22
	v_lshrrev_b32_e32 v25, 4, v25
	v_mul_u32_u24_e32 v34, 0x820, v26
	v_mul_u32_u24_e32 v26, 0x104, v214
	v_lshl_add_u32 v33, v25, 2, 0
	v_add_u32_e32 v26, v27, v26
	v_lshl_add_u64 v[20:21], s[20:21], 0, v[22:23]
	v_lshl_add_u64 v[22:23], s[14:15], 0, v[22:23]
	s_lshl_b32 s60, s99, 6
	s_movk_i32 s27, 64
	s_lshl_b32 s36, s99, 7
	s_movk_i32 s37, 128
	v_add_u32_e32 v27, 0x2080, v26
	v_add_u32_e32 v28, 0x2088, v26
	v_add_u32_e32 v29, 0x4100, v26
	v_add_u32_e32 v30, 0x4108, v26
	v_add_u32_e32 v31, 0x6180, v26
	v_add_u32_e32 v32, 0x6188, v26
	v_add_u32_e32 v24, v24, v34
	v_add_u32_e32 v33, v33, v34
	s_mov_b32 s62, s99
	s_branch .LBB0_63

; template <bool REMAP = false>
; __device__ __forceinline__ void transpose_convert(LAS unsigned char* lds, const float* src, bf16_t* dst, int K, int N, int G, int bid) {
;     ...
;     for (int t = bid; t < ntiles; t += G) {
;         const int k0 = (t / ntn) * 128, n0 = (t % ntn) * 64;
;         asm volatile("s_waitcnt lgkmcnt(0)" ::: "memory"); __builtin_amdgcn_s_barrier(); asm volatile("" ::: "memory");
; #pragma unroll
;         for (int i = 0; i < 4; ++i) {
; #pragma unroll
;             for (int j = 0; j < 4; ++j) tile[(r0 + 32 * i) * 65 + c4 * 4 + j] = v[i][j]; }
;         asm volatile("s_waitcnt lgkmcnt(0)" ::: "memory"); __builtin_amdgcn_s_barrier(); asm volatile("" ::: "memory");
;         if (t + G < ntiles) { const int k1 = ((t + G) / ntn) * 128, n1 = ((t + G) % ntn) * 64;
; #pragma unroll
;             for (int i = 0; i < 4; ++i) v[i] = __builtin_nontemporal_load((const f32x4*)(src + (size_t)(k1 + r0 + 32 * i) * N + n1 + c4 * 4)); }
.LBB0_63:
	s_waitcnt lgkmcnt(0)
	s_barrier
	s_waitcnt vmcnt(3)
	ds_write2_b32 v26, v0, v1 offset1:1
	ds_write2_b32 v26, v2, v3 offset0:2 offset1:3
	s_waitcnt vmcnt(2)
	ds_write2_b32 v27, v4, v5 offset1:1
	ds_write2_b32 v28, v6, v7 offset1:1
	s_waitcnt vmcnt(1)
	ds_write2_b32 v29, v8, v9 offset1:1
	ds_write2_b32 v30, v10, v11 offset1:1
	s_waitcnt vmcnt(0)
	ds_write2_b32 v31, v12, v13 offset1:1
	ds_write2_b32 v32, v14, v15 offset1:1
	s_waitcnt lgkmcnt(0)
	s_barrier
	s_add_i32 s61, s62, 1
	s_cmp_ge_i32 s61, s100
	s_cselect_b64 s[18:19], -1, 0
	s_cmp_lt_i32 s61, s100
	s_mov_b64 s[20:21], -1
	s_cbranch_scc1 .LBB0_65
	s_add_i32 s63, s60, s27
	s_mov_b64 s[20:21], 0
